# dil-16 attention loop unrolled x2 with swapped cur/nxt register sets (no v_mov_b64 copies), end-of-body vmcnt drains removed so the prefetch is two iterations deep
# baseline (speedup 1.0000x reference)
; __device__ __forceinline__ AttnLd attn_load(const bf16_t* __restrict__ ka, const bf16_t* __restrict__ va, int S, int r, int n0, int lane, int f) {
;     int dsh, cb; attn_geom(f, r, n0, dsh, cb);
;     const int qi = lane & 15, g = lane >> 4, rd = r & ((1 << dsh) - 1), ncls = S >> dsh;
; __device__ __forceinline__ void attn_item(const bf16_t* __restrict__ Z, const bf16_t* __restrict__ KA, const bf16_t* __restrict__ VA, bf16_t* __restrict__ MIX, int S, int it) {
;     ...
;         for (int f = 18; f < 23; ++f) {
;             const AttnLd nxt0 = attn_load(ka, va, S, rt[0], n0, lane, f < 22 ? f + 1 : 22), nxt1 = attn_load(ka, va, S, rt[1], n0, lane, f < 22 ? f + 1 : 22);
;             const int cb = n0 - 64 + 32 * (f - 18), ncls = S >> 4, cq = n0 + qi;
;             f32x4 sA0 = {0.f, 0.f, 0.f, 0.f}, sB0 = {0.f, 0.f, 0.f, 0.f}, sA1 = {0.f, 0.f, 0.f, 0.f}, sB1 = {0.f, 0.f, 0.f, 0.f};
;             sA0 = MFMA16(cur0.ka0, q0[0], sA0); sA1 = MFMA16(cur1.ka0, q0[1], sA1); sB0 = MFMA16(cur0.kb0, q0[0], sB0); sB1 = MFMA16(cur1.kb0, q0[1], sB1);
;             sA0 = MFMA16(cur0.ka1, q1[0], sA0); sA1 = MFMA16(cur1.ka1, q1[1], sA1); sB0 = MFMA16(cur0.kb1, q1[0], sB0); sB1 = MFMA16(cur1.kb1, q1[1], sB1);
;             LDS_FENCE();
;             { bf16_t* d = Vs + (lane >> 3) * 68 + 8 * (lane & 7);
;               *(u32x2*)d = (u32x2){cur0.v0.x, cur0.v0.y}; *(u32x2*)(d + 4) = (u32x2){cur0.v0.z, cur0.v0.w};
;               *(u32x2*)(d + 8 * 68) = (u32x2){cur0.v1.x, cur0.v1.y}; *(u32x2*)(d + 8 * 68 + 4) = (u32x2){cur0.v1.z, cur0.v1.w};
;               *(u32x2*)(d + 16 * 68) = (u32x2){cur0.v2.x, cur0.v2.y}; *(u32x2*)(d + 16 * 68 + 4) = (u32x2){cur0.v2.z, cur0.v2.w};
;               *(u32x2*)(d + 24 * 68) = (u32x2){cur0.v3.x, cur0.v3.y}; *(u32x2*)(d + 24 * 68 + 4) = (u32x2){cur0.v3.z, cur0.v3.w};
;               d = Vs1 + (lane >> 3) * 68 + 8 * (lane & 7);
;               *(u32x2*)d = (u32x2){cur1.v0.x, cur1.v0.y}; *(u32x2*)(d + 4) = (u32x2){cur1.v0.z, cur1.v0.w};
;               *(u32x2*)(d + 8 * 68) = (u32x2){cur1.v1.x, cur1.v1.y}; *(u32x2*)(d + 8 * 68 + 4) = (u32x2){cur1.v1.z, cur1.v1.w};
;               *(u32x2*)(d + 16 * 68) = (u32x2){cur1.v2.x, cur1.v2.y}; *(u32x2*)(d + 16 * 68 + 4) = (u32x2){cur1.v2.z, cur1.v2.w};
;               *(u32x2*)(d + 24 * 68) = (u32x2){cur1.v3.x, cur1.v3.y}; *(u32x2*)(d + 24 * 68 + 4) = (u32x2){cur1.v3.z, cur1.v3.w}; }
.LBB0_401:
	s_cmpk_lg_i32 s15, 0x80
	s_cselect_b32 s19, s18, 22
	s_cmp_lt_u32 s19, 18
	s_cselect_b32 s20, 2, 4
	s_add_i32 s22, s19, -12
	s_cmp_lt_u32 s22, 6
	s_cselect_b32 s22, -12, 0xffffffee
	s_cmp_gt_u32 s19, 11
	s_cselect_b32 s20, s20, 0
	s_cselect_b32 s22, s22, 0
	s_add_i32 s22, s22, s19
	s_lshr_b32 s19, 16, s20
	s_mul_i32 s19, s19, s3
	s_lshl_b32 s22, s22, 5
	s_add_i32 s19, s19, s22
	v_ashrrev_i32_e32 v48, s20, v182
	s_sub_i32 s19, s19, 64
	v_add_u32_e32 v52, s19, v48
	s_lshr_b32 s23, s79, s20
	v_add_u32_e32 v48, v52, v220
	s_lshl_b32 s22, -1, s20
	v_max_i32_e32 v49, 0, v48
	s_add_i32 s23, s23, -1
	v_max_i32_e32 v48, -4, v48
	v_bitop3_b32 v53, v182, s22, v182 bitop3:0x30
	v_min_u32_e32 v49, s23, v49
	v_add_u32_e32 v48, 4, v48
	v_min_u32_e32 v50, s23, v48
	v_lshl_add_u32 v178, v49, s20, v53
	v_lshlrev_b64 v[48:49], 7, v[178:179]
	v_lshl_add_u32 v178, v50, s20, v53
	v_lshlrev_b64 v[50:51], 7, v[178:179]
	v_lshl_add_u64 v[48:49], v[190:191], 0, v[48:49]
	v_lshl_add_u64 v[50:51], v[190:191], 0, v[50:51]
	global_load_dwordx4 v[56:59], v[48:49], off
	global_load_dwordx4 v[60:63], v[48:49], off offset:64
	global_load_dwordx4 v[88:91], v[50:51], off
	global_load_dwordx4 v[92:95], v[50:51], off offset:64
	v_add_u32_e32 v50, v52, v221
	v_max_i32_e32 v48, 0, v50
	v_min_u32_e32 v48, s23, v48
	v_lshl_add_u32 v178, v48, s20, v53
	v_lshlrev_b64 v[48:49], 7, v[178:179]
	v_lshl_add_u64 v[48:49], v[188:189], 0, v[48:49]
	global_load_dwordx4 v[96:99], v[48:49], off
	v_max_i32_e32 v48, -8, v50
	v_add_u32_e32 v48, 8, v48
	v_min_u32_e32 v48, s23, v48
	v_lshl_add_u32 v178, v48, s20, v53
	v_lshlrev_b64 v[48:49], 7, v[178:179]
	v_lshl_add_u64 v[48:49], v[188:189], 0, v[48:49]
	global_load_dwordx4 v[100:103], v[48:49], off
	v_max_i32_e32 v48, -16, v50
	v_add_u32_e32 v48, 16, v48
	v_min_u32_e32 v48, s23, v48
	v_lshl_add_u32 v178, v48, s20, v53
	v_lshlrev_b64 v[48:49], 7, v[178:179]
	v_lshl_add_u64 v[48:49], v[188:189], 0, v[48:49]
	global_load_dwordx4 v[104:107], v[48:49], off
	v_max_i32_e32 v48, 0xffffffe8, v50
	v_add_u32_e32 v48, 24, v48
	v_min_u32_e32 v48, s23, v48
	v_lshl_add_u32 v178, v48, s20, v53
	v_lshlrev_b64 v[48:49], 7, v[178:179]
	v_lshl_add_u64 v[48:49], v[188:189], 0, v[48:49]
	global_load_dwordx4 v[108:111], v[48:49], off
	v_ashrrev_i32_e32 v48, s20, v180
	v_add_u32_e32 v72, s19, v48
	v_add_u32_e32 v48, v72, v220
	v_max_i32_e32 v49, 0, v48
	v_max_i32_e32 v48, -4, v48
	v_bitop3_b32 v84, v180, s22, v180 bitop3:0x30
	v_min_u32_e32 v49, s23, v49
	v_add_u32_e32 v48, 4, v48
	v_add_u32_e32 v85, v72, v221
	v_min_u32_e32 v50, s23, v48
	v_lshl_add_u32 v178, v49, s20, v84
	v_max_i32_e32 v72, 0, v85
	v_max_i32_e32 v76, -8, v85
	v_lshlrev_b64 v[48:49], 7, v[178:179]
	v_lshl_add_u32 v178, v50, s20, v84
	v_min_u32_e32 v72, s23, v72
	v_add_u32_e32 v76, 8, v76
	v_max_i32_e32 v80, -16, v85
	v_lshl_add_u64 v[52:53], v[190:191], 0, v[48:49]
	v_lshlrev_b64 v[48:49], 7, v[178:179]
	v_lshl_add_u32 v178, v72, s20, v84
	v_min_u32_e32 v76, s23, v76
	v_add_u32_e32 v80, 16, v80
	v_max_i32_e32 v85, 0xffffffe8, v85
	v_lshlrev_b64 v[72:73], 7, v[178:179]
	v_lshl_add_u32 v178, v76, s20, v84
	v_min_u32_e32 v80, s23, v80
	v_add_u32_e32 v85, 24, v85
	s_waitcnt vmcnt(21)
	v_mfma_f32_16x16x32_bf16 v[124:127], v[124:127], v[40:43], 0
	v_lshlrev_b64 v[76:77], 7, v[178:179]
	v_lshl_add_u32 v178, v80, s20, v84
	v_min_u32_e32 v85, s23, v85
	v_lshlrev_b64 v[80:81], 7, v[178:179]
	v_lshl_add_u32 v178, v85, s20, v84
	v_lshlrev_b64 v[84:85], 7, v[178:179]
	v_lshl_add_u64 v[68:69], v[190:191], 0, v[48:49]
	v_lshl_add_u64 v[72:73], v[188:189], 0, v[72:73]
	v_lshl_add_u64 v[76:77], v[188:189], 0, v[76:77]
	v_lshl_add_u64 v[80:81], v[188:189], 0, v[80:81]
	v_lshl_add_u64 v[84:85], v[188:189], 0, v[84:85]
	s_waitcnt vmcnt(20)
	v_mfma_f32_16x16x32_bf16 v[120:123], v[120:123], v[44:47], v[124:127]
	global_load_dwordx4 v[48:51], v[52:53], off
	s_nop 0
	global_load_dwordx4 v[52:55], v[52:53], off offset:64
	s_nop 0
	global_load_dwordx4 v[64:67], v[68:69], off
	s_nop 0
	global_load_dwordx4 v[68:71], v[68:69], off offset:64
	v_add_u32_e32 v124, 0x880, v222
	global_load_dwordx4 v[72:75], v[72:73], off
	v_mfma_f32_16x16x32_bf16 v[140:143], v[140:143], v[40:43], 0
	global_load_dwordx4 v[76:79], v[76:77], off
	v_mov_b32_e32 v226, v183
	global_load_dwordx4 v[80:83], v[80:81], off
	v_mfma_f32_16x16x32_bf16 v[136:139], v[136:139], v[44:47], v[140:143]
	global_load_dwordx4 v[84:87], v[84:85], off
	s_waitcnt lgkmcnt(0)
	s_waitcnt vmcnt(27)
	ds_write2_b64 v222, v[132:133], v[134:135] offset1:1
	s_waitcnt vmcnt(26)
	ds_write2_b64 v222, v[128:129], v[130:131] offset0:136 offset1:137
	s_waitcnt vmcnt(25)
	ds_write2_b64 v124, v[116:117], v[118:119] offset1:1
	v_add_u32_e32 v116, 0xcc0, v222
	s_waitcnt vmcnt(24)
	ds_write2_b64 v116, v[112:113], v[114:115] offset1:1
	v_add_u32_e32 v112, 0x8800, v222
	s_waitcnt vmcnt(19)
	ds_write2_b64 v112, v[156:157], v[158:159] offset1:1
	v_add_u32_e32 v112, 0x8c40, v222
	s_waitcnt vmcnt(18)
	ds_write2_b64 v112, v[148:149], v[150:151] offset1:1
	v_add_u32_e32 v112, 0x9080, v222
	s_waitcnt vmcnt(17)
	ds_write2_b64 v112, v[152:153], v[154:155] offset1:1
	v_add_u32_e32 v112, 0x94c0, v222
	s_waitcnt vmcnt(16)
; __device__ __forceinline__ float xmax16(float m) { auto rr = __builtin_amdgcn_permlane16_swap(__float_as_uint(m), __float_as_uint(m), false, false); return fmaxf(__uint_as_float(rr[0]), __uint_as_float(rr[1])); }
; __device__ __forceinline__ float xmax32(float m) { auto rr = __builtin_amdgcn_permlane32_swap(__float_as_uint(m), __float_as_uint(m), false, false); return fmaxf(__uint_as_float(rr[0]), __uint_as_float(rr[1])); }
; #define LDS_FENCE() asm volatile("s_waitcnt lgkmcnt(0)" ::: "memory")
; #define MFMA16(a, b, c) __builtin_amdgcn_mfma_f32_16x16x32_bf16((a), (b), (c), 0, 0, 0)
; __device__ __forceinline__ bf16x8 attn_softmax_step(const f32x4& sA, const f32x4& sB, int cb, int cq, int ncls, int g, float& m, float& lsum, f32x4 (&O)[4]) {
;     float s[8]; bool ok[8];
;     const int c0v = cb + 8 * g, d0 = c0v - cq + 64;
; #pragma unroll
;     for (int j = 0; j < 8; ++j) {
;         ok[j] = ((unsigned)(c0v + j) < (unsigned)ncls) && ((unsigned)(d0 + j) <= 128u);
;         s[j] = ok[j] ? (j < 4 ? sA[j] : sB[j - 4]) : -__builtin_inff(); }
;     float mx = fmaxf(fmaxf(fmaxf(s[0], s[1]), fmaxf(s[2], s[3])), fmaxf(fmaxf(s[4], s[5]), fmaxf(s[6], s[7])));
;     mx = xmax32(xmax16(mx));
;     const float mn = fmaxf(m, mx), alpha = __builtin_amdgcn_exp2f(m - mn);
;     m = mn;
;     float pj[8], ps_ = 0.f;
; #pragma unroll
;     for (int j = 0; j < 8; ++j) { pj[j] = __builtin_amdgcn_exp2f(s[j] - mn); ps_ += pj[j]; }
;     lsum = lsum * alpha + ps_;
; #pragma unroll
;     for (int nbk = 0; nbk < 4; ++nbk) O[nbk] *= alpha;
;     return pack8(pj);
; __device__ __forceinline__ void attn_item(const bf16_t* __restrict__ Z, const bf16_t* __restrict__ KA, const bf16_t* __restrict__ VA, bf16_t* __restrict__ MIX, int S, int it) {
;     ...
;             const bf16x8 P0_ = attn_softmax_step(sA0, sB0, cb, cq, ncls, g, m[0], lsum[0], O[0]);
;             const bf16x8 P1_ = attn_softmax_step(sA1, sB1, cb, cq, ncls, g, m[1], lsum[1], O[1]);
;             LDS_FENCE();
; #pragma unroll
;             for (int nbk = 0; nbk < 4; ++nbk) { O[0][nbk] = MFMA16(gather8(Vs + (8 * g) * 68 + 16 * nbk, 68, qi), P0_, O[0][nbk]); O[1][nbk] = MFMA16(gather8(Vs1 + (8 * g) * 68 + 16 * nbk, 68, qi), P1_, O[1][nbk]); }
	ds_write2_b64 v112, v[144:145], v[146:147] offset1:1
	v_add_u32_e32 v112, s15, v224
	v_subrev_u32_e32 v113, 64, v112
	v_add_u32_e32 v114, s15, v225
	v_cmp_gt_u32_e32 vcc, s91, v113
	v_cmp_gt_u32_e64 s[36:37], s78, v114
	v_subrev_u32_e32 v115, 63, v112
	s_and_b64 vcc, vcc, s[36:37]
	v_cmp_gt_u32_e64 s[36:37], s91, v115
	v_add_u32_e32 v115, 1, v114
	v_cmp_gt_u32_e64 s[38:39], s78, v115
	v_subrev_u32_e32 v116, 62, v112
	s_and_b64 s[36:37], s[36:37], s[38:39]
	v_cmp_gt_u32_e64 s[38:39], s91, v116
	v_add_u32_e32 v116, 2, v114
	v_cmp_gt_u32_e64 s[40:41], s78, v116
	v_subrev_u32_e32 v116, 61, v112
	s_and_b64 s[38:39], s[38:39], s[40:41]
	v_cmp_gt_u32_e64 s[40:41], s91, v116
	v_add_u32_e32 v116, 3, v114
	v_cmp_gt_u32_e64 s[42:43], s78, v116
	v_subrev_u32_e32 v116, 60, v112
	s_and_b64 s[40:41], s[40:41], s[42:43]
	v_cmp_gt_u32_e64 s[42:43], s91, v116
	v_add_u32_e32 v116, 4, v114
	v_cmp_gt_u32_e64 s[44:45], s78, v116
	v_subrev_u32_e32 v116, 59, v112
	s_and_b64 s[42:43], s[42:43], s[44:45]
	v_cmp_gt_u32_e64 s[44:45], s91, v116
	v_add_u32_e32 v116, 5, v114
	v_cmp_gt_u32_e64 s[46:47], s78, v116
	v_subrev_u32_e32 v116, 58, v112
	s_and_b64 s[44:45], s[44:45], s[46:47]
	v_cmp_gt_u32_e64 s[46:47], s91, v116
	v_add_u32_e32 v116, 6, v114
	v_cmp_gt_u32_e64 s[48:49], s78, v116
	v_subrev_u32_e32 v112, 57, v112
	s_and_b64 s[46:47], s[46:47], s[48:49]
	v_cmp_gt_u32_e64 s[48:49], s91, v112
	v_add_u32_e32 v112, 7, v114
	v_cndmask_b32_e32 v113, v205, v136, vcc
	v_cndmask_b32_e64 v115, v205, v137, s[36:37]
	v_cmp_gt_u32_e64 s[50:51], s78, v112
	v_cndmask_b32_e64 v117, v205, v138, s[38:39]
	v_cndmask_b32_e64 v119, v205, v139, s[40:41]
	s_and_b64 s[48:49], s[48:49], s[50:51]
	v_cndmask_b32_e64 v125, v205, v122, s[46:47]
	v_cndmask_b32_e64 v112, v205, v123, s[48:49]
	v_max_f32_e32 v114, v113, v115
	v_cndmask_b32_e64 v124, v205, v120, s[42:43]
	v_max_f32_e32 v116, v117, v119
	v_cndmask_b32_e64 v121, v205, v121, s[44:45]
	v_max_f32_e32 v118, v125, v112
	v_max3_f32 v118, v124, v121, v118
	v_max3_f32 v114, v114, v116, v118
	v_mov_b32_e32 v116, v114
	s_nop 1
	v_permlane16_swap_b32_e32 v114, v116
	v_mfma_f32_16x16x32_bf16 v[172:175], v[172:175], v[0:3], 0
	v_max_f32_e32 v114, v114, v116
	v_mov_b32_e32 v116, v114
	s_nop 1
	v_permlane32_swap_b32_e32 v114, v116
	v_mfma_f32_16x16x32_bf16 v[164:167], v[164:167], v[0:3], 0
	v_max3_f32 v183, v226, v114, v116
	v_sub_f32_e32 v114, v226, v183
	v_sub_f32_e32 v113, v113, v183
	v_mfma_f32_16x16x32_bf16 v[140:143], v[168:171], v[4:7], v[172:175]
	v_exp_f32_e32 v116, v113
	v_sub_f32_e32 v113, v115, v183
	v_exp_f32_e32 v132, v114
	v_mfma_f32_16x16x32_bf16 v[160:163], v[160:163], v[4:7], v[164:167]
	v_exp_f32_e32 v118, v113
	v_sub_f32_e32 v113, v117, v183
	v_exp_f32_e32 v120, v113
	v_sub_f32_e32 v113, v119, v183
	v_exp_f32_e32 v122, v113
	v_sub_f32_e32 v113, v124, v183
	v_cndmask_b32_e32 v117, v205, v140, vcc
	v_cndmask_b32_e64 v119, v205, v141, s[36:37]
	v_exp_f32_e32 v124, v113
	v_sub_f32_e32 v113, v121, v183
	v_pk_mul_f32 v[30:31], v[30:31], v[132:133] op_sel_hi:[1,0]
	v_pk_mul_f32 v[28:29], v[28:29], v[132:133] op_sel_hi:[1,0]
	v_pk_mul_f32 v[26:27], v[26:27], v[132:133] op_sel_hi:[1,0]
	v_pk_mul_f32 v[24:25], v[24:25], v[132:133] op_sel_hi:[1,0]
	v_pk_mul_f32 v[34:35], v[34:35], v[132:133] op_sel_hi:[1,0]
	v_pk_mul_f32 v[32:33], v[32:33], v[132:133] op_sel_hi:[1,0]
	v_pk_mul_f32 v[38:39], v[38:39], v[132:133] op_sel_hi:[1,0]
	v_pk_mul_f32 v[36:37], v[36:37], v[132:133] op_sel_hi:[1,0]
	v_cndmask_b32_e64 v121, v205, v142, s[38:39]
	v_cndmask_b32_e64 v123, v205, v143, s[40:41]
	v_cndmask_b32_e64 v129, v205, v162, s[46:47]
	v_cndmask_b32_e64 v131, v205, v163, s[48:49]
	v_max_f32_e32 v133, v117, v119
	v_max_f32_e32 v134, v121, v123
	v_exp_f32_e32 v126, v113
	v_sub_f32_e32 v113, v125, v183
	v_cndmask_b32_e64 v125, v205, v160, s[42:43]
	v_cndmask_b32_e64 v127, v205, v161, s[44:45]
	v_max_f32_e32 v135, v129, v131
	v_max3_f32 v135, v125, v127, v135
	v_max3_f32 v133, v133, v134, v135
	v_mov_b32_e32 v134, v133
	s_nop 1
	v_permlane16_swap_b32_e32 v133, v134
	v_max_f32_e32 v133, v133, v134
	v_mov_b32_e32 v134, v133
	s_nop 1
	v_permlane32_swap_b32_e32 v133, v134
	v_mov_b32_e32 v135, v177
	v_max3_f32 v177, v135, v133, v134
	v_sub_f32_e32 v117, v117, v177
	v_exp_f32_e32 v117, v117
	v_sub_f32_e32 v119, v119, v177
	v_exp_f32_e32 v119, v119
	v_sub_f32_e32 v121, v121, v177
	v_sub_f32_e32 v133, v135, v177
	v_exp_f32_e32 v121, v121
	v_sub_f32_e32 v123, v123, v177
	v_exp_f32_e32 v123, v123
	v_sub_f32_e32 v125, v125, v177
	v_sub_f32_e32 v127, v127, v177
	v_exp_f32_e32 v133, v133
	v_exp_f32_e32 v125, v125
	v_exp_f32_e32 v127, v127
	v_pk_add_f32 v[134:135], v[116:117], 0 op_sel_hi:[1,0]
	v_sub_f32_e32 v112, v112, v183
	v_pk_add_f32 v[134:135], v[118:119], v[134:135]
	v_exp_f32_e32 v128, v113
	v_pk_add_f32 v[134:135], v[120:121], v[134:135]
	v_exp_f32_e32 v130, v112
	v_cvt_pk_bf16_f32 v112, v116, v118
	v_pk_add_f32 v[134:135], v[122:123], v[134:135]
	v_mov_b32_e32 v116, v133
	s_waitcnt lgkmcnt(0)
	v_cvt_pk_bf16_f32 v113, v120, v122
	v_cvt_pk_bf16_f32 v114, v124, v126
	v_pk_add_f32 v[134:135], v[124:125], v[134:135]
	v_pk_mul_f32 v[18:19], v[18:19], v[116:117] op_sel_hi:[1,0]
	v_pk_mul_f32 v[16:17], v[16:17], v[116:117] op_sel_hi:[1,0]
	v_pk_mul_f32 v[10:11], v[10:11], v[116:117] op_sel_hi:[1,0]
	v_pk_mul_f32 v[8:9], v[8:9], v[116:117] op_sel_hi:[1,0]
	v_pk_mul_f32 v[22:23], v[22:23], v[116:117] op_sel_hi:[1,0]
	v_pk_mul_f32 v[20:21], v[20:21], v[116:117] op_sel_hi:[1,0]
	v_pk_mul_f32 v[14:15], v[14:15], v[116:117] op_sel_hi:[1,0]
	v_pk_mul_f32 v[12:13], v[12:13], v[116:117] op_sel_hi:[1,0]
	v_cvt_pk_bf16_f32 v116, v117, v119
	v_cvt_pk_bf16_f32 v117, v121, v123
	v_cvt_pk_bf16_f32 v118, v125, v127
	ds_read_b64_tr_b16 v[122:123], v223 offset:544
	ds_read_b64_tr_b16 v[120:121], v223
	ds_read_b64_tr_b16 v[124:125], v223 offset:32
	v_cvt_pk_bf16_f32 v115, v128, v130
	v_sub_f32_e32 v129, v129, v177
	v_sub_f32_e32 v131, v131, v177
	v_exp_f32_e32 v129, v129
	v_exp_f32_e32 v131, v131
	s_waitcnt lgkmcnt(1)
; #define LDS_FENCE() asm volatile("s_waitcnt lgkmcnt(0)" ::: "memory")
; __device__ __forceinline__ void attn_item(const bf16_t* __restrict__ Z, const bf16_t* __restrict__ KA, const bf16_t* __restrict__ VA, bf16_t* __restrict__ MIX, int S, int it) {
;     ...
;         for (int f = 18; f < 23; ++f) {
;             const AttnLd nxt0 = attn_load(ka, va, S, rt[0], n0, lane, f < 22 ? f + 1 : 22), nxt1 = attn_load(ka, va, S, rt[1], n0, lane, f < 22 ? f + 1 : 22);
;             const int cb = n0 - 64 + 32 * (f - 18), ncls = S >> 4, cq = n0 + qi;
;             f32x4 sA0 = {0.f, 0.f, 0.f, 0.f}, sB0 = {0.f, 0.f, 0.f, 0.f}, sA1 = {0.f, 0.f, 0.f, 0.f}, sB1 = {0.f, 0.f, 0.f, 0.f};
;             sA0 = MFMA16(cur0.ka0, q0[0], sA0); sA1 = MFMA16(cur1.ka0, q0[1], sA1); sB0 = MFMA16(cur0.kb0, q0[0], sB0); sB1 = MFMA16(cur1.kb0, q0[1], sB1);
;             sA0 = MFMA16(cur0.ka1, q1[0], sA0); sA1 = MFMA16(cur1.ka1, q1[1], sA1); sB0 = MFMA16(cur0.kb1, q1[0], sB0); sB1 = MFMA16(cur1.kb1, q1[1], sB1);
;             LDS_FENCE();
;             { bf16_t* d = Vs + (lane >> 3) * 68 + 8 * (lane & 7);
;               *(u32x2*)d = (u32x2){cur0.v0.x, cur0.v0.y}; *(u32x2*)(d + 4) = (u32x2){cur0.v0.z, cur0.v0.w};
;               *(u32x2*)(d + 8 * 68) = (u32x2){cur0.v1.x, cur0.v1.y}; *(u32x2*)(d + 8 * 68 + 4) = (u32x2){cur0.v1.z, cur0.v1.w};
;               *(u32x2*)(d + 16 * 68) = (u32x2){cur0.v2.x, cur0.v2.y}; *(u32x2*)(d + 16 * 68 + 4) = (u32x2){cur0.v2.z, cur0.v2.w};
;               *(u32x2*)(d + 24 * 68) = (u32x2){cur0.v3.x, cur0.v3.y}; *(u32x2*)(d + 24 * 68 + 4) = (u32x2){cur0.v3.z, cur0.v3.w};
;               d = Vs1 + (lane >> 3) * 68 + 8 * (lane & 7);
;               *(u32x2*)d = (u32x2){cur1.v0.x, cur1.v0.y}; *(u32x2*)(d + 4) = (u32x2){cur1.v0.z, cur1.v0.w};
;               *(u32x2*)(d + 8 * 68) = (u32x2){cur1.v1.x, cur1.v1.y}; *(u32x2*)(d + 8 * 68 + 4) = (u32x2){cur1.v1.z, cur1.v1.w};
;               *(u32x2*)(d + 16 * 68) = (u32x2){cur1.v2.x, cur1.v2.y}; *(u32x2*)(d + 16 * 68 + 4) = (u32x2){cur1.v2.z, cur1.v2.w};
;               *(u32x2*)(d + 24 * 68) = (u32x2){cur1.v3.x, cur1.v3.y}; *(u32x2*)(d + 24 * 68 + 4) = (u32x2){cur1.v3.z, cur1.v3.w}; }
;             const bf16x8 P0_ = attn_softmax_step(sA0, sB0, cb, cq, ncls, g, m[0], lsum[0], O[0]);
;             const bf16x8 P1_ = attn_softmax_step(sA1, sB1, cb, cq, ncls, g, m[1], lsum[1], O[1]);
;             LDS_FENCE();
; #pragma unroll
	v_mfma_f32_16x16x32_bf16 v[28:31], v[120:123], v[112:115], v[28:31]
	ds_read_b64_tr_b16 v[120:121], v223 offset:34816
	ds_read_b64_tr_b16 v[122:123], v223 offset:35360
	v_pk_add_f32 v[134:135], v[126:127], v[134:135]
	v_cvt_pk_bf16_f32 v119, v129, v131
	ds_read_b64_tr_b16 v[126:127], v223 offset:576
	s_waitcnt lgkmcnt(0)
	v_mfma_f32_16x16x32_bf16 v[24:27], v[124:127], v[112:115], v[24:27]
	v_add_f32_e64 v134, v128, v134
	v_add_f32_e64 v135, v129, v135
	s_add_i32 s15, s15, 32
	v_pk_add_f32 v[134:135], v[130:131], v[134:135]
	v_mfma_f32_16x16x32_bf16 v[16:19], v[120:123], v[116:119], v[16:19]
	ds_read_b64_tr_b16 v[120:121], v223 offset:34848
	ds_read_b64_tr_b16 v[122:123], v223 offset:35392
	v_pk_fma_f32 v[184:185], v[184:185], v[132:133], v[134:135]
	s_add_i32 s18, s18, 1
	s_waitcnt lgkmcnt(0)
	v_mfma_f32_16x16x32_bf16 v[8:11], v[120:123], v[116:119], v[8:11]
	ds_read_b64_tr_b16 v[120:121], v223 offset:64
	ds_read_b64_tr_b16 v[122:123], v223 offset:608
	s_waitcnt lgkmcnt(0)
	v_mfma_f32_16x16x32_bf16 v[32:35], v[120:123], v[112:115], v[32:35]
	ds_read_b64_tr_b16 v[120:121], v223 offset:34880
	ds_read_b64_tr_b16 v[122:123], v223 offset:35424
	s_waitcnt lgkmcnt(0)
	v_mfma_f32_16x16x32_bf16 v[20:23], v[120:123], v[116:119], v[20:23]
	ds_read_b64_tr_b16 v[120:121], v223 offset:96
	ds_read_b64_tr_b16 v[122:123], v223 offset:640
	s_waitcnt lgkmcnt(0)
	v_mfma_f32_16x16x32_bf16 v[36:39], v[120:123], v[112:115], v[36:39]
	ds_read_b64_tr_b16 v[112:113], v223 offset:34912
	ds_read_b64_tr_b16 v[114:115], v223 offset:35456
	s_waitcnt lgkmcnt(0)
	v_mfma_f32_16x16x32_bf16 v[12:15], v[112:115], v[116:119], v[12:15]
	s_cmpk_eq_i32 s15, 0xa0
	s_cbranch_scc1 .Lmy_d16_exit
	s_cmpk_lg_i32 s15, 0x80
	s_cselect_b32 s19, s18, 22
	s_cmp_lt_u32 s19, 18
	s_cselect_b32 s20, 2, 4
	s_add_i32 s22, s19, -12
	s_cmp_lt_u32 s22, 6
	s_cselect_b32 s22, -12, 0xffffffee
	s_cmp_gt_u32 s19, 11
	s_cselect_b32 s20, s20, 0
	s_cselect_b32 s22, s22, 0
	s_add_i32 s22, s22, s19
	s_lshr_b32 s19, 16, s20
	s_mul_i32 s19, s19, s3
	s_lshl_b32 s22, s22, 5
	s_add_i32 s19, s19, s22
	v_ashrrev_i32_e32 v172, s20, v182
	s_sub_i32 s19, s19, 64
	v_add_u32_e32 v168, s19, v172
	s_lshr_b32 s23, s79, s20
	v_add_u32_e32 v172, v168, v220
	s_lshl_b32 s22, -1, s20
	v_max_i32_e32 v173, 0, v172
	s_add_i32 s23, s23, -1
	v_max_i32_e32 v172, -4, v172
	v_bitop3_b32 v169, v182, s22, v182 bitop3:0x30
	v_min_u32_e32 v173, s23, v173
	v_add_u32_e32 v172, 4, v172
	v_min_u32_e32 v174, s23, v172
	v_lshl_add_u32 v178, v173, s20, v169
	v_lshlrev_b64 v[172:173], 7, v[178:179]
	v_lshl_add_u32 v178, v174, s20, v169
	v_lshlrev_b64 v[174:175], 7, v[178:179]
	v_lshl_add_u64 v[172:173], v[190:191], 0, v[172:173]
	v_lshl_add_u64 v[174:175], v[190:191], 0, v[174:175]
	global_load_dwordx4 v[140:143], v[172:173], off
	global_load_dwordx4 v[136:139], v[172:173], off offset:64
	global_load_dwordx4 v[124:127], v[174:175], off
	global_load_dwordx4 v[120:123], v[174:175], off offset:64
	v_add_u32_e32 v174, v168, v221
	v_max_i32_e32 v172, 0, v174
	v_min_u32_e32 v172, s23, v172
	v_lshl_add_u32 v178, v172, s20, v169
	v_lshlrev_b64 v[172:173], 7, v[178:179]
	v_lshl_add_u64 v[172:173], v[188:189], 0, v[172:173]
	global_load_dwordx4 v[132:135], v[172:173], off
	v_max_i32_e32 v172, -8, v174
	v_add_u32_e32 v172, 8, v172
	v_min_u32_e32 v172, s23, v172
	v_lshl_add_u32 v178, v172, s20, v169
	v_lshlrev_b64 v[172:173], 7, v[178:179]
	v_lshl_add_u64 v[172:173], v[188:189], 0, v[172:173]
	global_load_dwordx4 v[128:131], v[172:173], off
	v_max_i32_e32 v172, -16, v174
	v_add_u32_e32 v172, 16, v172
	v_min_u32_e32 v172, s23, v172
	v_lshl_add_u32 v178, v172, s20, v169
	v_lshlrev_b64 v[172:173], 7, v[178:179]
	v_lshl_add_u64 v[172:173], v[188:189], 0, v[172:173]
	global_load_dwordx4 v[116:119], v[172:173], off
	v_max_i32_e32 v172, 0xffffffe8, v174
	v_add_u32_e32 v172, 24, v172
	v_min_u32_e32 v172, s23, v172
	v_lshl_add_u32 v178, v172, s20, v169
	v_lshlrev_b64 v[172:173], 7, v[178:179]
	v_lshl_add_u64 v[172:173], v[188:189], 0, v[172:173]
	global_load_dwordx4 v[112:115], v[172:173], off
	v_ashrrev_i32_e32 v172, s20, v180
	v_add_u32_e32 v156, s19, v172
	v_add_u32_e32 v172, v156, v220
	v_max_i32_e32 v173, 0, v172
	v_max_i32_e32 v172, -4, v172
	v_bitop3_b32 v144, v180, s22, v180 bitop3:0x30
	v_min_u32_e32 v173, s23, v173
	v_add_u32_e32 v172, 4, v172
	v_add_u32_e32 v145, v156, v221
	v_min_u32_e32 v174, s23, v172
	v_lshl_add_u32 v178, v173, s20, v144
	v_max_i32_e32 v156, 0, v145
	v_max_i32_e32 v148, -8, v145
	v_lshlrev_b64 v[172:173], 7, v[178:179]
	v_lshl_add_u32 v178, v174, s20, v144
	v_min_u32_e32 v156, s23, v156
	v_add_u32_e32 v148, 8, v148
	v_max_i32_e32 v152, -16, v145
	v_lshl_add_u64 v[168:169], v[190:191], 0, v[172:173]
	v_lshlrev_b64 v[172:173], 7, v[178:179]
	v_lshl_add_u32 v178, v156, s20, v144
	v_min_u32_e32 v148, s23, v148
	v_add_u32_e32 v152, 16, v152
	v_max_i32_e32 v145, 0xffffffe8, v145
	v_lshlrev_b64 v[156:157], 7, v[178:179]
	v_lshl_add_u32 v178, v148, s20, v144
	v_min_u32_e32 v152, s23, v152
	v_add_u32_e32 v145, 24, v145
	s_waitcnt vmcnt(21)
	v_mfma_f32_16x16x32_bf16 v[88:91], v[88:91], v[40:43], 0
	v_lshlrev_b64 v[148:149], 7, v[178:179]
	v_lshl_add_u32 v178, v152, s20, v144
	v_min_u32_e32 v145, s23, v145
	v_lshlrev_b64 v[152:153], 7, v[178:179]
	v_lshl_add_u32 v178, v145, s20, v144
	v_lshlrev_b64 v[144:145], 7, v[178:179]
	v_lshl_add_u64 v[160:161], v[190:191], 0, v[172:173]
	v_lshl_add_u64 v[156:157], v[188:189], 0, v[156:157]
	v_lshl_add_u64 v[148:149], v[188:189], 0, v[148:149]
	v_lshl_add_u64 v[152:153], v[188:189], 0, v[152:153]
	v_lshl_add_u64 v[144:145], v[188:189], 0, v[144:145]
	s_waitcnt vmcnt(20)
; __device__ __forceinline__ bf16x8 attn_softmax_step(const f32x4& sA, const f32x4& sB, int cb, int cq, int ncls, int g, float& m, float& lsum, f32x4 (&O)[4]) {
;     float s[8]; bool ok[8];
;     const int c0v = cb + 8 * g, d0 = c0v - cq + 64;
; #pragma unroll
;     for (int j = 0; j < 8; ++j) {
;         ok[j] = ((unsigned)(c0v + j) < (unsigned)ncls) && ((unsigned)(d0 + j) <= 128u);
;         s[j] = ok[j] ? (j < 4 ? sA[j] : sB[j - 4]) : -__builtin_inff(); }
; __device__ __forceinline__ void attn_item(const bf16_t* __restrict__ Z, const bf16_t* __restrict__ KA, const bf16_t* __restrict__ VA, bf16_t* __restrict__ MIX, int S, int it) {
;     ...
;             sA0 = MFMA16(cur0.ka0, q0[0], sA0); sA1 = MFMA16(cur1.ka0, q0[1], sA1); sB0 = MFMA16(cur0.kb0, q0[0], sB0); sB1 = MFMA16(cur1.kb0, q0[1], sB1);
;             sA0 = MFMA16(cur0.ka1, q1[0], sA0); sA1 = MFMA16(cur1.ka1, q1[1], sA1); sB0 = MFMA16(cur0.kb1, q1[0], sB0); sB1 = MFMA16(cur1.kb1, q1[1], sB1);
;             LDS_FENCE();
;             { bf16_t* d = Vs + (lane >> 3) * 68 + 8 * (lane & 7);
;               *(u32x2*)d = (u32x2){cur0.v0.x, cur0.v0.y}; *(u32x2*)(d + 4) = (u32x2){cur0.v0.z, cur0.v0.w};
;               *(u32x2*)(d + 8 * 68) = (u32x2){cur0.v1.x, cur0.v1.y}; *(u32x2*)(d + 8 * 68 + 4) = (u32x2){cur0.v1.z, cur0.v1.w};
;               *(u32x2*)(d + 16 * 68) = (u32x2){cur0.v2.x, cur0.v2.y}; *(u32x2*)(d + 16 * 68 + 4) = (u32x2){cur0.v2.z, cur0.v2.w};
;               *(u32x2*)(d + 24 * 68) = (u32x2){cur0.v3.x, cur0.v3.y}; *(u32x2*)(d + 24 * 68 + 4) = (u32x2){cur0.v3.z, cur0.v3.w};
;               d = Vs1 + (lane >> 3) * 68 + 8 * (lane & 7);
;               *(u32x2*)d = (u32x2){cur1.v0.x, cur1.v0.y}; *(u32x2*)(d + 4) = (u32x2){cur1.v0.z, cur1.v0.w};
;               *(u32x2*)(d + 8 * 68) = (u32x2){cur1.v1.x, cur1.v1.y}; *(u32x2*)(d + 8 * 68 + 4) = (u32x2){cur1.v1.z, cur1.v1.w};
;               *(u32x2*)(d + 16 * 68) = (u32x2){cur1.v2.x, cur1.v2.y}; *(u32x2*)(d + 16 * 68 + 4) = (u32x2){cur1.v2.z, cur1.v2.w};
;               *(u32x2*)(d + 24 * 68) = (u32x2){cur1.v3.x, cur1.v3.y}; *(u32x2*)(d + 24 * 68 + 4) = (u32x2){cur1.v3.z, cur1.v3.w}; }
;             const bf16x8 P0_ = attn_softmax_step(sA0, sB0, cb, cq, ncls, g, m[0], lsum[0], O[0]);
;             const bf16x8 P1_ = attn_softmax_step(sA1, sB1, cb, cq, ncls, g, m[1], lsum[1], O[1]);
;             LDS_FENCE();
	v_mfma_f32_16x16x32_bf16 v[92:95], v[92:95], v[44:47], v[88:91]
	global_load_dwordx4 v[172:175], v[168:169], off
	s_nop 0
	global_load_dwordx4 v[168:171], v[168:169], off offset:64
	s_nop 0
	global_load_dwordx4 v[164:167], v[160:161], off
	s_nop 0
	global_load_dwordx4 v[160:163], v[160:161], off offset:64
	v_add_u32_e32 v88, 0x880, v222
	global_load_dwordx4 v[156:159], v[156:157], off
	v_mfma_f32_16x16x32_bf16 v[56:59], v[56:59], v[40:43], 0
	global_load_dwordx4 v[148:151], v[148:149], off
	v_mov_b32_e32 v226, v183
	global_load_dwordx4 v[152:155], v[152:153], off
	v_mfma_f32_16x16x32_bf16 v[60:63], v[60:63], v[44:47], v[56:59]
	global_load_dwordx4 v[144:147], v[144:145], off
	s_waitcnt lgkmcnt(0)
	s_waitcnt vmcnt(27)
	ds_write2_b64 v222, v[96:97], v[98:99] offset1:1
	s_waitcnt vmcnt(26)
	ds_write2_b64 v222, v[100:101], v[102:103] offset0:136 offset1:137
	s_waitcnt vmcnt(25)
	ds_write2_b64 v88, v[104:105], v[106:107] offset1:1
	v_add_u32_e32 v104, 0xcc0, v222
	s_waitcnt vmcnt(24)
	ds_write2_b64 v104, v[108:109], v[110:111] offset1:1
	v_add_u32_e32 v108, 0x8800, v222
	s_waitcnt vmcnt(19)
	ds_write2_b64 v108, v[72:73], v[74:75] offset1:1
	v_add_u32_e32 v108, 0x8c40, v222
	s_waitcnt vmcnt(18)
	ds_write2_b64 v108, v[76:77], v[78:79] offset1:1
	v_add_u32_e32 v108, 0x9080, v222
	s_waitcnt vmcnt(17)
	ds_write2_b64 v108, v[80:81], v[82:83] offset1:1
	v_add_u32_e32 v108, 0x94c0, v222
	s_waitcnt vmcnt(16)
	ds_write2_b64 v108, v[84:85], v[86:87] offset1:1
	v_add_u32_e32 v108, s15, v224
	v_subrev_u32_e32 v109, 64, v108
	v_add_u32_e32 v110, s15, v225
	v_cmp_gt_u32_e32 vcc, s91, v109
	v_cmp_gt_u32_e64 s[36:37], s78, v110
	v_subrev_u32_e32 v111, 63, v108
	s_and_b64 vcc, vcc, s[36:37]
	v_cmp_gt_u32_e64 s[36:37], s91, v111
	v_add_u32_e32 v111, 1, v110
	v_cmp_gt_u32_e64 s[38:39], s78, v111
	v_subrev_u32_e32 v104, 62, v108
	s_and_b64 s[36:37], s[36:37], s[38:39]
	v_cmp_gt_u32_e64 s[38:39], s91, v104
	v_add_u32_e32 v104, 2, v110
	v_cmp_gt_u32_e64 s[40:41], s78, v104
	v_subrev_u32_e32 v104, 61, v108
	s_and_b64 s[38:39], s[38:39], s[40:41]
	v_cmp_gt_u32_e64 s[40:41], s91, v104
	v_add_u32_e32 v104, 3, v110
	v_cmp_gt_u32_e64 s[42:43], s78, v104
	v_subrev_u32_e32 v104, 60, v108
	s_and_b64 s[40:41], s[40:41], s[42:43]
	v_cmp_gt_u32_e64 s[42:43], s91, v104
	v_add_u32_e32 v104, 4, v110
	v_cmp_gt_u32_e64 s[44:45], s78, v104
	v_subrev_u32_e32 v104, 59, v108
	s_and_b64 s[42:43], s[42:43], s[44:45]
	v_cmp_gt_u32_e64 s[44:45], s91, v104
	v_add_u32_e32 v104, 5, v110
	v_cmp_gt_u32_e64 s[46:47], s78, v104
	v_subrev_u32_e32 v104, 58, v108
	s_and_b64 s[44:45], s[44:45], s[46:47]
	v_cmp_gt_u32_e64 s[46:47], s91, v104
	v_add_u32_e32 v104, 6, v110
	v_cmp_gt_u32_e64 s[48:49], s78, v104
	v_subrev_u32_e32 v108, 57, v108
	s_and_b64 s[46:47], s[46:47], s[48:49]
	v_cmp_gt_u32_e64 s[48:49], s91, v108
	v_add_u32_e32 v108, 7, v110
	v_cndmask_b32_e32 v109, v205, v60, vcc
	v_cndmask_b32_e64 v111, v205, v61, s[36:37]
	v_cmp_gt_u32_e64 s[50:51], s78, v108
	v_cndmask_b32_e64 v105, v205, v62, s[38:39]
	v_cndmask_b32_e64 v107, v205, v63, s[40:41]
	s_and_b64 s[48:49], s[48:49], s[50:51]
	v_cndmask_b32_e64 v89, v205, v94, s[46:47]
	v_cndmask_b32_e64 v108, v205, v95, s[48:49]
	v_max_f32_e32 v110, v109, v111
	v_cndmask_b32_e64 v88, v205, v92, s[42:43]
	v_max_f32_e32 v104, v105, v107
	v_cndmask_b32_e64 v93, v205, v93, s[44:45]
	v_max_f32_e32 v106, v89, v108
	v_max3_f32 v106, v88, v93, v106
	v_max3_f32 v110, v110, v104, v106
	v_mov_b32_e32 v104, v110
	s_nop 1
	v_permlane16_swap_b32_e32 v110, v104
	v_mfma_f32_16x16x32_bf16 v[48:51], v[48:51], v[0:3], 0
	v_max_f32_e32 v110, v110, v104
	v_mov_b32_e32 v104, v110
	s_nop 1
	v_permlane32_swap_b32_e32 v110, v104
	v_mfma_f32_16x16x32_bf16 v[64:67], v[64:67], v[0:3], 0
	v_max3_f32 v183, v226, v110, v104
	v_sub_f32_e32 v110, v226, v183
	v_sub_f32_e32 v109, v109, v183
	v_mfma_f32_16x16x32_bf16 v[56:59], v[52:55], v[4:7], v[48:51]
	v_exp_f32_e32 v104, v109
	v_sub_f32_e32 v109, v111, v183
	v_exp_f32_e32 v96, v110
	v_mfma_f32_16x16x32_bf16 v[68:71], v[68:71], v[4:7], v[64:67]
	v_exp_f32_e32 v106, v109
	v_sub_f32_e32 v109, v105, v183
	v_exp_f32_e32 v92, v109
	v_sub_f32_e32 v109, v107, v183
	v_exp_f32_e32 v94, v109
	v_sub_f32_e32 v109, v88, v183
	v_cndmask_b32_e32 v105, v205, v56, vcc
	v_cndmask_b32_e64 v107, v205, v57, s[36:37]
	v_exp_f32_e32 v88, v109
	v_sub_f32_e32 v109, v93, v183
	v_pk_mul_f32 v[30:31], v[30:31], v[96:97] op_sel_hi:[1,0]
	v_pk_mul_f32 v[28:29], v[28:29], v[96:97] op_sel_hi:[1,0]
	v_pk_mul_f32 v[26:27], v[26:27], v[96:97] op_sel_hi:[1,0]
	v_pk_mul_f32 v[24:25], v[24:25], v[96:97] op_sel_hi:[1,0]
	v_pk_mul_f32 v[34:35], v[34:35], v[96:97] op_sel_hi:[1,0]
	v_pk_mul_f32 v[32:33], v[32:33], v[96:97] op_sel_hi:[1,0]
	v_pk_mul_f32 v[38:39], v[38:39], v[96:97] op_sel_hi:[1,0]
	v_pk_mul_f32 v[36:37], v[36:37], v[96:97] op_sel_hi:[1,0]
	v_cndmask_b32_e64 v93, v205, v58, s[38:39]
	v_cndmask_b32_e64 v95, v205, v59, s[40:41]
	v_cndmask_b32_e64 v101, v205, v70, s[46:47]
	v_cndmask_b32_e64 v103, v205, v71, s[48:49]
	v_max_f32_e32 v97, v105, v107
	v_max_f32_e32 v98, v93, v95
	v_exp_f32_e32 v90, v109
	v_sub_f32_e32 v109, v89, v183
	v_cndmask_b32_e64 v89, v205, v68, s[42:43]
	v_cndmask_b32_e64 v91, v205, v69, s[44:45]
	v_max_f32_e32 v99, v101, v103
	v_max3_f32 v99, v89, v91, v99
	v_max3_f32 v97, v97, v98, v99
	v_mov_b32_e32 v98, v97
	s_nop 1
	v_permlane16_swap_b32_e32 v97, v98
	v_max_f32_e32 v97, v97, v98
	v_mov_b32_e32 v98, v97
	s_nop 1
	v_permlane32_swap_b32_e32 v97, v98
	v_mov_b32_e32 v99, v177
	v_max3_f32 v177, v99, v97, v98
	v_sub_f32_e32 v105, v105, v177
	v_exp_f32_e32 v105, v105
	v_sub_f32_e32 v107, v107, v177
	v_exp_f32_e32 v107, v107
	v_sub_f32_e32 v93, v93, v177
	v_sub_f32_e32 v97, v99, v177
	v_exp_f32_e32 v93, v93
	v_sub_f32_e32 v95, v95, v177
	v_exp_f32_e32 v95, v95
	v_sub_f32_e32 v89, v89, v177
	v_sub_f32_e32 v91, v91, v177
	v_exp_f32_e32 v97, v97
	v_exp_f32_e32 v89, v89
	v_exp_f32_e32 v91, v91
	v_pk_add_f32 v[98:99], v[104:105], 0 op_sel_hi:[1,0]
	v_sub_f32_e32 v108, v108, v183
	v_pk_add_f32 v[98:99], v[106:107], v[98:99]
	v_exp_f32_e32 v100, v109
	v_pk_add_f32 v[98:99], v[92:93], v[98:99]
	v_exp_f32_e32 v102, v108
	v_cvt_pk_bf16_f32 v108, v104, v106
	v_pk_add_f32 v[98:99], v[94:95], v[98:99]
	v_mov_b32_e32 v104, v97
	s_waitcnt lgkmcnt(0)
; #define LDS_FENCE() asm volatile("s_waitcnt lgkmcnt(0)" ::: "memory")
; #define MFMA16(a, b, c) __builtin_amdgcn_mfma_f32_16x16x32_bf16((a), (b), (c), 0, 0, 0)
; __device__ __forceinline__ void attn_item(const bf16_t* __restrict__ Z, const bf16_t* __restrict__ KA, const bf16_t* __restrict__ VA, bf16_t* __restrict__ MIX, int S, int it) {
;     ...
;             const bf16x8 P0_ = attn_softmax_step(sA0, sB0, cb, cq, ncls, g, m[0], lsum[0], O[0]);
;             const bf16x8 P1_ = attn_softmax_step(sA1, sB1, cb, cq, ncls, g, m[1], lsum[1], O[1]);
;             LDS_FENCE();
; #pragma unroll
;             for (int nbk = 0; nbk < 4; ++nbk) { O[0][nbk] = MFMA16(gather8(Vs + (8 * g) * 68 + 16 * nbk, 68, qi), P0_, O[0][nbk]); O[1][nbk] = MFMA16(gather8(Vs1 + (8 * g) * 68 + 16 * nbk, 68, qi), P1_, O[1][nbk]); }
;             cur0 = nxt0; cur1 = nxt1;
;         }
;         LDS_FENCE();
;     }
;     __syncthreads();
;     attn_stage<400>(ka, va, Kt, Vt, P0 - 64, S, 0, 0, tid);
	v_cvt_pk_bf16_f32 v109, v92, v94
	v_cvt_pk_bf16_f32 v110, v88, v90
	v_pk_add_f32 v[98:99], v[88:89], v[98:99]
	v_pk_mul_f32 v[18:19], v[18:19], v[104:105] op_sel_hi:[1,0]
	v_pk_mul_f32 v[16:17], v[16:17], v[104:105] op_sel_hi:[1,0]
	v_pk_mul_f32 v[10:11], v[10:11], v[104:105] op_sel_hi:[1,0]
	v_pk_mul_f32 v[8:9], v[8:9], v[104:105] op_sel_hi:[1,0]
	v_pk_mul_f32 v[22:23], v[22:23], v[104:105] op_sel_hi:[1,0]
	v_pk_mul_f32 v[20:21], v[20:21], v[104:105] op_sel_hi:[1,0]
	v_pk_mul_f32 v[14:15], v[14:15], v[104:105] op_sel_hi:[1,0]
	v_pk_mul_f32 v[12:13], v[12:13], v[104:105] op_sel_hi:[1,0]
	v_cvt_pk_bf16_f32 v104, v105, v107
	v_cvt_pk_bf16_f32 v105, v93, v95
	v_cvt_pk_bf16_f32 v106, v89, v91
	ds_read_b64_tr_b16 v[94:95], v223 offset:544
	ds_read_b64_tr_b16 v[92:93], v223
	ds_read_b64_tr_b16 v[88:89], v223 offset:32
	v_cvt_pk_bf16_f32 v111, v100, v102
	v_sub_f32_e32 v101, v101, v177
	v_sub_f32_e32 v103, v103, v177
	v_exp_f32_e32 v101, v101
	v_exp_f32_e32 v103, v103
	s_waitcnt lgkmcnt(1)
	v_mfma_f32_16x16x32_bf16 v[28:31], v[92:95], v[108:111], v[28:31]
	ds_read_b64_tr_b16 v[92:93], v223 offset:34816
	ds_read_b64_tr_b16 v[94:95], v223 offset:35360
	v_pk_add_f32 v[98:99], v[90:91], v[98:99]
	v_cvt_pk_bf16_f32 v107, v101, v103
	ds_read_b64_tr_b16 v[90:91], v223 offset:576
	s_waitcnt lgkmcnt(0)
	v_mfma_f32_16x16x32_bf16 v[24:27], v[88:91], v[108:111], v[24:27]
	v_add_f32_e64 v98, v100, v98
	v_add_f32_e64 v99, v101, v99
	s_add_i32 s15, s15, 32
	v_pk_add_f32 v[98:99], v[102:103], v[98:99]
	v_mfma_f32_16x16x32_bf16 v[16:19], v[92:95], v[104:107], v[16:19]
	ds_read_b64_tr_b16 v[92:93], v223 offset:34848
	ds_read_b64_tr_b16 v[94:95], v223 offset:35392
	v_pk_fma_f32 v[184:185], v[184:185], v[96:97], v[98:99]
	s_add_i32 s18, s18, 1
	s_waitcnt lgkmcnt(0)
	v_mfma_f32_16x16x32_bf16 v[8:11], v[92:95], v[104:107], v[8:11]
	ds_read_b64_tr_b16 v[92:93], v223 offset:64
	ds_read_b64_tr_b16 v[94:95], v223 offset:608
	s_waitcnt lgkmcnt(0)
	v_mfma_f32_16x16x32_bf16 v[32:35], v[92:95], v[108:111], v[32:35]
	ds_read_b64_tr_b16 v[92:93], v223 offset:34880
	ds_read_b64_tr_b16 v[94:95], v223 offset:35424
	s_waitcnt lgkmcnt(0)
	v_mfma_f32_16x16x32_bf16 v[20:23], v[92:95], v[104:107], v[20:23]
	ds_read_b64_tr_b16 v[92:93], v223 offset:96
	ds_read_b64_tr_b16 v[94:95], v223 offset:640
	s_waitcnt lgkmcnt(0)
	v_mfma_f32_16x16x32_bf16 v[36:39], v[92:95], v[108:111], v[36:39]
	ds_read_b64_tr_b16 v[108:109], v223 offset:34912
	ds_read_b64_tr_b16 v[110:111], v223 offset:35456
	s_waitcnt lgkmcnt(0)
	v_mfma_f32_16x16x32_bf16 v[12:15], v[108:111], v[104:107], v[12:15]
	s_cmpk_eq_i32 s15, 0xa0
	s_cbranch_scc0 .LBB0_401
.Lmy_d16_exit:
	s_waitcnt vmcnt(0)
	v_min_i32_e32 v52, 0x18ff, v187
	s_sub_i32 s3, s12, 64
	v_ashrrev_i32_e32 v124, 4, v52
	v_add_u32_e32 v48, s3, v124
	v_max_i32_e32 v48, 0, v48
	v_and_b32_e32 v125, 8, v52
	v_min_u32_e32 v178, s90, v48
	v_mov_b32_e32 v99, s95
	v_mov_b32_e32 v100, s7
	v_cmp_eq_u32_e32 vcc, 0, v125
	v_mov_b32_e32 v122, s94
	v_mov_b32_e32 v123, s6
	v_cndmask_b32_e32 v49, v99, v100, vcc
	v_cndmask_b32_e32 v48, v122, v123, vcc
	v_lshlrev_b64 v[50:51], 7, v[178:179]
	v_min_i32_e32 v56, 0x16ff, v187
	v_lshl_add_u64 v[48:49], v[48:49], 0, v[50:51]
	v_lshlrev_b32_e32 v50, 4, v52
	v_add_u32_e32 v52, 0x200, v56
	v_ashrrev_i32_e32 v126, 4, v52
	v_add_u32_e32 v52, s3, v126
	v_max_i32_e32 v52, 0, v52
	v_and_b32_e32 v127, 8, v56
	v_min_u32_e32 v52, s90, v52
	v_cmp_eq_u32_e64 s[36:37], 0, v127
	v_mov_b32_e32 v53, v179
	v_lshlrev_b64 v[52:53], 7, v[52:53]
	v_cndmask_b32_e64 v55, v99, v100, s[36:37]
	v_cndmask_b32_e64 v54, v122, v123, s[36:37]
	v_lshl_add_u64 v[52:53], v[54:55], 0, v[52:53]
	v_lshlrev_b32_e32 v54, 4, v56
	v_and_b32_e32 v56, 0x70, v54
	v_mov_b32_e32 v57, v179
	v_lshl_add_u64 v[52:53], v[52:53], 0, v[56:57]
	v_min_i32_e32 v57, 0x14ff, v187
	v_add_u32_e32 v58, 0x400, v57
	v_ashrrev_i32_e32 v128, 4, v58
	v_add_u32_e32 v58, s3, v128
	v_max_i32_e32 v58, 0, v58
	v_and_b32_e32 v129, 8, v57
	v_min_u32_e32 v58, s90, v58
	v_cmp_eq_u32_e64 s[38:39], 0, v129
	v_mov_b32_e32 v59, v179
	v_lshlrev_b32_e32 v57, 4, v57
	v_cndmask_b32_e64 v61, v99, v100, s[38:39]
	v_cndmask_b32_e64 v60, v122, v123, s[38:39]
	v_lshlrev_b64 v[58:59], 7, v[58:59]
	v_and_b32_e32 v102, 0x70, v57
	v_min_i32_e32 v57, 0x12ff, v187
	v_lshl_add_u64 v[58:59], v[60:61], 0, v[58:59]
	v_mov_b32_e32 v103, v179
	v_add_u32_e32 v62, 0x600, v57
	v_lshl_add_u64 v[58:59], v[58:59], 0, v[102:103]
	v_ashrrev_i32_e32 v103, 4, v62
	v_add_u32_e32 v62, s3, v103
	v_max_i32_e32 v62, 0, v62
	v_and_b32_e32 v130, 8, v57
	v_min_u32_e32 v62, s90, v62
	v_cmp_eq_u32_e64 s[40:41], 0, v130
	v_mov_b32_e32 v63, v179
	v_lshlrev_b32_e32 v57, 4, v57
	v_cndmask_b32_e64 v65, v99, v100, s[40:41]
	v_cndmask_b32_e64 v64, v122, v123, s[40:41]
	v_lshlrev_b64 v[62:63], 7, v[62:63]
	v_and_b32_e32 v104, 0x70, v57
	v_min_i32_e32 v57, 0x10ff, v187
	v_lshl_add_u64 v[62:63], v[64:65], 0, v[62:63]
	v_mov_b32_e32 v105, v179
	v_add_u32_e32 v66, 0x800, v57
	v_lshl_add_u64 v[62:63], v[62:63], 0, v[104:105]
	v_ashrrev_i32_e32 v105, 4, v66
	v_add_u32_e32 v66, s3, v105
	v_max_i32_e32 v66, 0, v66
	v_and_b32_e32 v131, 8, v57
	v_min_u32_e32 v66, s90, v66
	v_cmp_eq_u32_e64 s[42:43], 0, v131
	v_mov_b32_e32 v67, v179
	v_lshlrev_b32_e32 v57, 4, v57
	v_cndmask_b32_e64 v69, v99, v100, s[42:43]
	v_cndmask_b32_e64 v68, v122, v123, s[42:43]
	v_lshlrev_b64 v[66:67], 7, v[66:67]
	v_and_b32_e32 v106, 0x70, v57
	v_min_i32_e32 v57, 0xeff, v187
	v_lshl_add_u64 v[66:67], v[68:69], 0, v[66:67]
	v_mov_b32_e32 v107, v179
	v_add_u32_e32 v70, 0xa00, v57
	v_lshl_add_u64 v[66:67], v[66:67], 0, v[106:107]
	v_ashrrev_i32_e32 v107, 4, v70
	v_add_u32_e32 v70, s3, v107
	v_max_i32_e32 v70, 0, v70
	v_and_b32_e32 v132, 8, v57
	v_min_u32_e32 v70, s90, v70
	v_cmp_eq_u32_e64 s[44:45], 0, v132
	v_mov_b32_e32 v71, v179
	v_lshlrev_b32_e32 v57, 4, v57
	v_cndmask_b32_e64 v73, v99, v100, s[44:45]
	v_cndmask_b32_e64 v72, v122, v123, s[44:45]
	v_lshlrev_b64 v[70:71], 7, v[70:71]
	v_and_b32_e32 v108, 0x70, v57
	v_min_i32_e32 v57, 0xcff, v187
	v_lshl_add_u64 v[70:71], v[72:73], 0, v[70:71]
	v_mov_b32_e32 v109, v179
	v_add_u32_e32 v74, 0xc00, v57
	v_lshl_add_u64 v[70:71], v[70:71], 0, v[108:109]
	v_ashrrev_i32_e32 v109, 4, v74
	v_add_u32_e32 v74, s3, v109
	v_and_b32_e32 v178, 0x70, v50
	v_max_i32_e32 v74, 0, v74
	v_and_b32_e32 v133, 8, v57
	v_lshl_add_u64 v[48:49], v[48:49], 0, v[178:179]
	v_min_u32_e32 v74, s90, v74
	v_cmp_eq_u32_e64 s[46:47], 0, v133
	v_mov_b32_e32 v75, v179
	v_lshlrev_b32_e32 v57, 4, v57
	s_waitcnt lgkmcnt(0)
	s_barrier
; template <int NROWS>
; __device__ __forceinline__ void attn_stage(const bf16_t* __restrict__ ka, const bf16_t* __restrict__ va, bf16_t* Kt, bf16_t* Vt, int c0, int ncls, int rd, int dsh, int tid) {
;     ...
;     for (int u = 0; u < IT; ++u) { const int idx = min(tid + u * NTHR, NROWS * 16 - 1);
;         const int i = idx >> 4, ch = idx & 15, isv = ch >> 3, c8 = ch & 7; const int c = min(max(c0 + i, 0), ncls - 1);
;         v[u] = *(const u32x4*)((isv ? va : ka) + (size_t)(rd + (c << dsh)) * 64 + 8 * c8); }
; #pragma unroll
;     for (int u = 0; u < IT; ++u) { const int idx = min(tid + u * NTHR, NROWS * 16 - 1);
;         const int i = idx >> 4, ch = idx & 15, isv = ch >> 3, c8 = ch & 7;
;         bf16_t* d = isv ? (Vt + i * 68 + 8 * c8) : (Kt + i * 72 + 8 * c8);
;         *(u32x2*)d = (u32x2){v[u].x, v[u].y}; *(u32x2*)(d + 4) = (u32x2){v[u].z, v[u].w}; }
; __device__ __forceinline__ void attn_item(const bf16_t* __restrict__ Z, const bf16_t* __restrict__ KA, const bf16_t* __restrict__ VA, bf16_t* __restrict__ MIX, int S, int it) {
;     ...
;     attn_stage<400>(ka, va, Kt, Vt, P0 - 64, S, 0, 0, tid);
	global_load_dwordx4 v[48:51], v[48:49], off
	v_cndmask_b32_e64 v77, v99, v100, s[46:47]
	v_cndmask_b32_e64 v76, v122, v123, s[46:47]
	v_lshlrev_b64 v[74:75], 7, v[74:75]
	v_and_b32_e32 v110, 0x70, v57
	v_min_i32_e32 v57, 0xaff, v187
	v_lshl_add_u64 v[74:75], v[76:77], 0, v[74:75]
	v_mov_b32_e32 v111, v179
	v_add_u32_e32 v78, 0xe00, v57
	v_lshl_add_u64 v[74:75], v[74:75], 0, v[110:111]
	v_ashrrev_i32_e32 v111, 4, v78
	global_load_dwordx4 v[52:55], v[52:53], off
	v_add_u32_e32 v78, s3, v111
	v_max_i32_e32 v78, 0, v78
	v_and_b32_e32 v134, 8, v57
	v_min_u32_e32 v78, s90, v78
	v_cmp_eq_u32_e64 s[48:49], 0, v134
	v_mov_b32_e32 v79, v179
	v_lshlrev_b32_e32 v57, 4, v57
	global_load_dwordx4 v[58:61], v[58:59], off
	v_cndmask_b32_e64 v81, v99, v100, s[48:49]
	v_cndmask_b32_e64 v80, v122, v123, s[48:49]
	v_lshlrev_b64 v[78:79], 7, v[78:79]
	v_and_b32_e32 v112, 0x70, v57
	v_min_i32_e32 v57, 0x8ff, v187
	v_lshl_add_u64 v[78:79], v[80:81], 0, v[78:79]
	v_mov_b32_e32 v113, v179
	v_add_u32_e32 v82, 0x1000, v57
	v_lshl_add_u64 v[78:79], v[78:79], 0, v[112:113]
	v_ashrrev_i32_e32 v113, 4, v82
	global_load_dwordx4 v[62:65], v[62:63], off
	v_add_u32_e32 v82, s3, v113
	v_max_i32_e32 v82, 0, v82
	v_and_b32_e32 v135, 8, v57
	v_min_u32_e32 v82, s90, v82
	v_cmp_eq_u32_e64 s[50:51], 0, v135
	v_mov_b32_e32 v83, v179
	v_lshlrev_b32_e32 v57, 4, v57
	global_load_dwordx4 v[66:69], v[66:67], off
	v_cndmask_b32_e64 v85, v99, v100, s[50:51]
	v_cndmask_b32_e64 v84, v122, v123, s[50:51]
	v_lshlrev_b64 v[82:83], 7, v[82:83]
	v_and_b32_e32 v114, 0x70, v57
	v_min_i32_e32 v57, 0x6ff, v187
	v_lshl_add_u64 v[82:83], v[84:85], 0, v[82:83]
	v_mov_b32_e32 v115, v179
	v_add_u32_e32 v86, 0x1200, v57
	v_lshl_add_u64 v[82:83], v[82:83], 0, v[114:115]
	v_ashrrev_i32_e32 v115, 4, v86
	global_load_dwordx4 v[70:73], v[70:71], off
	v_add_u32_e32 v86, s3, v115
	v_max_i32_e32 v86, 0, v86
	v_and_b32_e32 v136, 8, v57
	v_min_u32_e32 v86, s90, v86
	v_cmp_eq_u32_e64 s[52:53], 0, v136
	v_mov_b32_e32 v87, v179
	v_lshlrev_b32_e32 v57, 4, v57
	global_load_dwordx4 v[74:77], v[74:75], off
	v_cndmask_b32_e64 v89, v99, v100, s[52:53]
	v_cndmask_b32_e64 v88, v122, v123, s[52:53]
	v_lshlrev_b64 v[86:87], 7, v[86:87]
	v_and_b32_e32 v116, 0x70, v57
	v_min_i32_e32 v57, 0x4ff, v187
	v_lshl_add_u64 v[86:87], v[88:89], 0, v[86:87]
	v_mov_b32_e32 v117, v179
	v_add_u32_e32 v90, 0x1400, v57
	v_lshl_add_u64 v[86:87], v[86:87], 0, v[116:117]
	v_ashrrev_i32_e32 v117, 4, v90
	global_load_dwordx4 v[78:81], v[78:79], off
	v_add_u32_e32 v90, s3, v117
	v_max_i32_e32 v90, 0, v90
	v_and_b32_e32 v137, 8, v57
	v_min_u32_e32 v90, s90, v90
	v_cmp_eq_u32_e64 s[54:55], 0, v137
	v_mov_b32_e32 v91, v179
	v_lshlrev_b32_e32 v57, 4, v57
	global_load_dwordx4 v[82:85], v[82:83], off
	v_cndmask_b32_e64 v93, v99, v100, s[54:55]
	v_cndmask_b32_e64 v92, v122, v123, s[54:55]
	v_lshlrev_b64 v[90:91], 7, v[90:91]
	v_and_b32_e32 v118, 0x70, v57
	v_min_i32_e32 v57, 0x2ff, v187
	v_lshl_add_u64 v[90:91], v[92:93], 0, v[90:91]
	v_mov_b32_e32 v119, v179
	v_add_u32_e32 v94, 0x1600, v57
	v_lshl_add_u64 v[90:91], v[90:91], 0, v[118:119]
	v_ashrrev_i32_e32 v119, 4, v94
	global_load_dwordx4 v[86:89], v[86:87], off
	v_add_u32_e32 v94, s3, v119
	v_max_i32_e32 v94, 0, v94
	v_and_b32_e32 v138, 8, v57
	v_min_u32_e32 v94, s90, v94
	v_cmp_eq_u32_e64 s[56:57], 0, v138
	v_mov_b32_e32 v95, v179
	global_load_dwordx4 v[90:93], v[90:91], off
	v_cndmask_b32_e64 v97, v99, v100, s[56:57]
	v_cndmask_b32_e64 v96, v122, v123, s[56:57]
	v_lshlrev_b64 v[94:95], 7, v[94:95]
	v_lshlrev_b32_e32 v57, 4, v57
	v_lshl_add_u64 v[94:95], v[96:97], 0, v[94:95]
	v_and_b32_e32 v120, 0x70, v57
	v_mov_b32_e32 v121, v179
	v_min_i32_e32 v57, 0xff, v187
	v_lshl_add_u64 v[94:95], v[94:95], 0, v[120:121]
	v_add_u32_e32 v98, 0x1800, v57
	global_load_dwordx4 v[94:97], v[94:95], off
	v_ashrrev_i32_e32 v121, 4, v98
	v_add_u32_e32 v98, s3, v121
	v_and_b32_e32 v139, 8, v57
	v_max_i32_e32 v98, 0, v98
	v_cmp_eq_u32_e64 s[58:59], 0, v139
	v_min_u32_e32 v98, s90, v98
	v_lshlrev_b32_e32 v57, 4, v57
	v_cndmask_b32_e64 v101, v99, v100, s[58:59]
	v_mov_b32_e32 v99, v179
	v_cndmask_b32_e64 v100, v122, v123, s[58:59]
	v_lshlrev_b64 v[98:99], 7, v[98:99]
	v_lshl_add_u64 v[98:99], v[100:101], 0, v[98:99]
	v_and_b32_e32 v122, 0x70, v57
	v_mov_b32_e32 v123, v179
	v_lshl_add_u64 v[98:99], v[98:99], 0, v[122:123]
	global_load_dwordx4 v[98:101], v[98:99], off
	v_readlane_b32 s15, v255, 0
	v_sub_u32_e32 v57, 0x90, v125
	v_mul_lo_u32 v57, v57, v124
	v_mov_b32_e32 v123, s15
	v_cndmask_b32_e64 v125, v123, 0, vcc
	v_add3_u32 v57, v125, v57, v178
	s_waitcnt vmcnt(12)
	ds_write2_b64 v57, v[48:49], v[50:51] offset1:1
	v_sub_u32_e32 v48, 0x90, v127
	v_cndmask_b32_e64 v49, v123, 0, s[36:37]
	v_mul_lo_u32 v48, v126, v48
	v_add3_u32 v48, v49, v48, v56
	s_waitcnt vmcnt(11)
	ds_write2_b64 v48, v[52:53], v[54:55] offset1:1
	v_sub_u32_e32 v48, 0x90, v129
	v_cndmask_b32_e64 v49, v123, 0, s[38:39]
	v_mul_lo_u32 v48, v128, v48
	v_add3_u32 v48, v49, v48, v102
	s_waitcnt vmcnt(10)
	ds_write2_b64 v48, v[58:59], v[60:61] offset1:1
	v_sub_u32_e32 v48, 0x90, v130
	v_cndmask_b32_e64 v49, v123, 0, s[40:41]
	v_mul_lo_u32 v48, v103, v48
	v_add3_u32 v48, v49, v48, v104
	s_waitcnt vmcnt(9)
	ds_write2_b64 v48, v[62:63], v[64:65] offset1:1
	v_sub_u32_e32 v48, 0x90, v131
	v_cndmask_b32_e64 v49, v123, 0, s[42:43]
	v_mul_lo_u32 v48, v105, v48
	v_add3_u32 v48, v49, v48, v106
	s_waitcnt vmcnt(8)
	ds_write2_b64 v48, v[66:67], v[68:69] offset1:1
	v_sub_u32_e32 v48, 0x90, v132
	v_cndmask_b32_e64 v49, v123, 0, s[44:45]
	v_mul_lo_u32 v48, v107, v48
	v_add3_u32 v48, v49, v48, v108
	s_waitcnt vmcnt(7)
; template <int NROWS>
; __device__ __forceinline__ void attn_stage(const bf16_t* __restrict__ ka, const bf16_t* __restrict__ va, bf16_t* Kt, bf16_t* Vt, int c0, int ncls, int rd, int dsh, int tid) {
;     ...
;     for (int u = 0; u < IT; ++u) { const int idx = min(tid + u * NTHR, NROWS * 16 - 1);
;         const int i = idx >> 4, ch = idx & 15, isv = ch >> 3, c8 = ch & 7;
;         bf16_t* d = isv ? (Vt + i * 68 + 8 * c8) : (Kt + i * 72 + 8 * c8);
;         *(u32x2*)d = (u32x2){v[u].x, v[u].y}; *(u32x2*)(d + 4) = (u32x2){v[u].z, v[u].w}; }
; __device__ __forceinline__ void attn_item(const bf16_t* __restrict__ Z, const bf16_t* __restrict__ KA, const bf16_t* __restrict__ VA, bf16_t* __restrict__ MIX, int S, int it) {
;     ...
;     __syncthreads();
; #pragma unroll 1
;     for (int i2 = 0; i2 < 12; ++i2) {
;         attn_lds_step(Kt, Vt, rt[0] + 32 * i2, q0[0], q1[0], P0 + rt[0] - 64 + 32 * i2, P0 + rt[0] + 16 * qi, S, qi, g, m[0], lsum[0], O[0]);
;         attn_lds_step(Kt, Vt, rt[1] + 32 * i2, q0[1], q1[1], P0 + rt[1] - 64 + 32 * i2, P0 + rt[1] + 16 * qi, S, qi, g, m[1], lsum[1], O[1]);
;     }
	ds_write2_b64 v48, v[70:71], v[72:73] offset1:1
	v_sub_u32_e32 v48, 0x90, v133
	v_cndmask_b32_e64 v49, v123, 0, s[46:47]
	v_mul_lo_u32 v48, v109, v48
	v_add3_u32 v48, v49, v48, v110
	s_waitcnt vmcnt(6)
	ds_write2_b64 v48, v[74:75], v[76:77] offset1:1
	v_sub_u32_e32 v48, 0x90, v134
	v_cndmask_b32_e64 v49, v123, 0, s[48:49]
	v_mul_lo_u32 v48, v111, v48
	v_add3_u32 v48, v49, v48, v112
	s_waitcnt vmcnt(5)
	ds_write2_b64 v48, v[78:79], v[80:81] offset1:1
	v_sub_u32_e32 v48, 0x90, v135
	v_cndmask_b32_e64 v49, v123, 0, s[50:51]
	v_mul_lo_u32 v48, v113, v48
	v_add3_u32 v48, v49, v48, v114
	s_waitcnt vmcnt(4)
	ds_write2_b64 v48, v[82:83], v[84:85] offset1:1
	v_sub_u32_e32 v48, 0x90, v136
	v_cndmask_b32_e64 v49, v123, 0, s[52:53]
	v_mul_lo_u32 v48, v115, v48
	v_add3_u32 v48, v49, v48, v116
	s_waitcnt vmcnt(3)
	ds_write2_b64 v48, v[86:87], v[88:89] offset1:1
	v_sub_u32_e32 v48, 0x90, v137
	v_cndmask_b32_e64 v49, v123, 0, s[54:55]
	v_mul_lo_u32 v48, v117, v48
	v_add3_u32 v48, v49, v48, v118
	s_waitcnt vmcnt(2)
	ds_write2_b64 v48, v[90:91], v[92:93] offset1:1
	v_sub_u32_e32 v48, 0x90, v138
	v_cndmask_b32_e64 v49, v123, 0, s[56:57]
	v_mul_lo_u32 v48, v119, v48
	v_add3_u32 v48, v49, v48, v120
	v_cndmask_b32_e64 v49, v123, 0, s[58:59]
	s_movk_i32 s15, 0x220
	s_waitcnt vmcnt(1)
	ds_write2_b64 v48, v[94:95], v[96:97] offset1:1
	v_sub_u32_e32 v48, 0x90, v139
	v_mul_lo_u32 v48, v121, v48
	v_add3_u32 v48, v49, v48, v122
	v_lshrrev_b32_e32 v49, 2, v217
	v_mul_u32_u24_e32 v94, 0x440, v218
	v_mul_lo_u32 v50, v49, s15
	v_mul_u32_u24_e32 v51, 0x88, v211
	v_add3_u32 v50, v94, v50, v51
	v_lshlrev_b32_e32 v96, 3, v212
	v_add3_u32 v76, v50, v96, v219
	s_movk_i32 s15, 0x240
	v_add_u32_e32 v50, v211, v212
	v_mul_u32_u24_e32 v95, 0x480, v214
	v_mul_lo_u32 v49, v49, s15
	v_mul_u32_u24_e32 v51, 0x90, v50
	s_waitcnt vmcnt(0)
	ds_write2_b64 v48, v[98:99], v[100:101] offset1:1
	v_lshlrev_b32_e32 v48, 1, v215
	v_add3_u32 v49, v95, v49, v51
	v_lshlrev_b32_e32 v52, 4, v218
	s_movk_i32 s15, 0x120
	v_and_b32_e32 v53, 24, v48
	v_add3_u32 v48, v186, v216, v211
	v_add3_u32 v77, v49, v52, s15
	s_movk_i32 s15, 0x88
	v_add_u32_e32 v74, s12, v48
	v_mul_lo_u32 v48, v48, s15
	v_add3_u32 v78, v48, v96, v219
	v_add3_u32 v48, v53, v216, v50
	s_movk_i32 s15, 0x90
	s_mov_b32 s3, 0
	v_mad_i32_i24 v75, v215, -16, v186
	v_mad_u64_u32 v[54:55], s[18:19], v48, s15, v[52:53]
	s_waitcnt lgkmcnt(0)
	s_barrier
	s_waitcnt vmcnt(0)
	v_mov_b32_e32 v100, v8
	v_mov_b32_e32 v101, v9
	v_mov_b32_e32 v102, v10
	v_mov_b32_e32 v103, v11
	v_mov_b32_e32 v104, v12
	v_mov_b32_e32 v105, v13
	v_mov_b32_e32 v106, v14
	v_mov_b32_e32 v107, v15
	v_mov_b32_e32 v108, v16
	v_mov_b32_e32 v109, v17
	v_mov_b32_e32 v110, v18
	v_mov_b32_e32 v111, v19
	v_mov_b32_e32 v112, v20
	v_mov_b32_e32 v113, v21
	v_mov_b32_e32 v114, v22
	v_mov_b32_e32 v115, v23
	v_mov_b32_e32 v116, v24
	v_mov_b32_e32 v117, v25
	v_mov_b32_e32 v118, v26
	v_mov_b32_e32 v119, v27
	v_mov_b32_e32 v120, v28
	v_mov_b32_e32 v121, v29
	v_mov_b32_e32 v122, v30
	v_mov_b32_e32 v123, v31
	v_mov_b32_e32 v124, v32
	v_mov_b32_e32 v125, v33
	v_mov_b32_e32 v126, v34
	v_mov_b32_e32 v127, v35
	v_mov_b32_e32 v128, v36
	v_mov_b32_e32 v129, v37
	v_mov_b32_e32 v130, v38
	v_mov_b32_e32 v131, v39
	v_mov_b32_e32 v132, v183
	v_mov_b32_e32 v133, v177
	v_mov_b32_e32 v134, v184
	v_mov_b32_e32 v135, v185
	v_mov_b32_e32 v136, v40
	v_mov_b32_e32 v137, v41
	v_mov_b32_e32 v138, v42
	v_mov_b32_e32 v139, v43
	v_mov_b32_e32 v140, v44
	v_mov_b32_e32 v141, v45
	v_mov_b32_e32 v142, v46
	v_mov_b32_e32 v143, v47
	v_mov_b32_e32 v144, v0
	v_mov_b32_e32 v145, v1
	v_mov_b32_e32 v146, v2
	v_mov_b32_e32 v147, v3
	v_mov_b32_e32 v148, v4
	v_mov_b32_e32 v149, v5
	v_mov_b32_e32 v150, v6
	v_mov_b32_e32 v151, v7
	v_mov_b32_e32 v8, 0
	v_mov_b32_e32 v9, 0
	v_mov_b32_e32 v10, 0
	v_mov_b32_e32 v11, 0
	v_mov_b32_e32 v12, 0
	v_mov_b32_e32 v13, 0
	v_mov_b32_e32 v14, 0
	v_mov_b32_e32 v15, 0
	v_mov_b32_e32 v16, 0
	v_mov_b32_e32 v17, 0
	v_mov_b32_e32 v18, 0
	v_mov_b32_e32 v19, 0
	v_mov_b32_e32 v20, 0
	v_mov_b32_e32 v21, 0
	v_mov_b32_e32 v22, 0
	v_mov_b32_e32 v23, 0
	v_mov_b32_e32 v24, 0
	v_mov_b32_e32 v25, 0
	v_mov_b32_e32 v26, 0
	v_mov_b32_e32 v27, 0
	v_mov_b32_e32 v28, 0
	v_mov_b32_e32 v29, 0
	v_mov_b32_e32 v30, 0
	v_mov_b32_e32 v31, 0
	v_mov_b32_e32 v32, 0
	v_mov_b32_e32 v33, 0
	v_mov_b32_e32 v34, 0
	v_mov_b32_e32 v35, 0
	v_mov_b32_e32 v36, 0
	v_mov_b32_e32 v37, 0
	v_mov_b32_e32 v38, 0
	v_mov_b32_e32 v39, 0
	v_mov_b32_e32 v183, 0xf149f2ca
	v_mov_b32_e32 v177, 0xf149f2ca
	v_mov_b32_e32 v184, 0
	v_mov_b32_e32 v185, 0
	v_mov_b32_e32 v40, v228
	v_mov_b32_e32 v41, v229
	v_mov_b32_e32 v42, v230
	v_mov_b32_e32 v43, v231
	v_mov_b32_e32 v44, v232
	v_mov_b32_e32 v45, v233
	v_mov_b32_e32 v46, v234
	v_mov_b32_e32 v47, v235
	v_mov_b32_e32 v0, v236
	v_mov_b32_e32 v1, v237
	v_mov_b32_e32 v2, v238
	v_mov_b32_e32 v3, v239
	v_mov_b32_e32 v4, v240
	v_mov_b32_e32 v5, v241
	v_mov_b32_e32 v6, v242
	v_mov_b32_e32 v7, v243
	v_and_b32_e32 v152, 63, v176
	v_and_b32_e32 v153, 15, v152
	v_lshrrev_b32_e32 v154, 4, v152
	v_lshrrev_b32_e32 v155, 6, v176
	v_lshrrev_b32_e32 v156, 2, v153
	v_and_b32_e32 v157, 3, v153
	v_lshrrev_b32_e32 v158, 1, v153
	v_and_b32_e32 v159, 1, v153
	v_lshlrev_b32_e32 v160, 5, v155
	v_lshl_add_u32 v161, v156, 3, v157
	v_add_u32_e32 v161, v160, v161
	v_mul_u32_u24_e32 v161, 0x90, v161
	v_lshl_add_u32 v54, v154, 4, v161
	v_add_u32_e32 v77, 0x120, v54
	v_lshl_add_u32 v162, v154, 3, v160
	v_add_u32_e32 v163, v162, v156
	v_mul_u32_u24_e32 v163, 0x88, v163
	v_lshl_add_u32 v78, v157, 3, v163
	v_mov_b32_e32 v76, v78
	v_add_u32_e32 v74, s12, v162
	v_lshl_add_u32 v164, v158, 2, v159
	v_lshlrev_b32_e32 v165, 3, v154
	v_sub_u32_e32 v75, v165, v164
	s_mov_b32 s3, 0
